# plus: ssm pass-3 scan loop prefetches u two bodies ahead (unrolled by two), chunk-carry chain loads 16 states per batch one batch ahead
# baseline (speedup 1.0000x reference)
; __device__ __forceinline__ unsigned cvt_pk_bf16(float lo, float hi) { unsigned r; asm volatile("v_cvt_pk_bf16_f32 %0, %1, %2" : "=v"(r) : "v"(lo), "v"(hi)); return r; }
; __device__ __forceinline__ void ssm_setup(CArgs* ap, const float* COEF, int l, int g, int p, float& abr, float& abi, float (&bbr)[16], float (&bbi)[16]) {
;     const f32x4 cf = *(const f32x4*)(COEF + (size_t)(g * 64 + p) * 4);
;     abr = cf[0]; abi = cf[1];
;     const float cr = cf[2], ci = cf[3];
;     const float* br = ap->in[14] + ((size_t)(l * 32 + g) * 64 + p) * 16; const float* bi = ap->in[15] + ((size_t)(l * 32 + g) * 64 + p) * 16;
; #pragma unroll
;     for (int q = 0; q < 4; ++q) { const f32x4 r4 = *(const f32x4*)(br + 4 * q), i4 = *(const f32x4*)(bi + 4 * q);
; #pragma unroll
;         for (int i = 0; i < 4; ++i) { bbr[4 * q + i] = cr * r4[i] - ci * i4[i]; bbi[4 * q + i] = cr * i4[i] + ci * r4[i]; } }
; }
; __device__ __forceinline__ void ssm_pass3h(CArgs* ap, const float* COEF, int l, const bf16_t* PROJ, const float* SST, bf16_t* YS, LAS unsigned char* wlds, int unit, int lane) {
;     ...
;     for (int k = 0; k < 8; ++k) { bbr2[k] = cvt_pk_bf16(bbr[2 * k], bbr[2 * k + 1]); bbi2[k] = cvt_pk_bf16(bbi[2 * k], bbi[2 * k + 1]); }
;     float cmB[32];
; #pragma unroll
;     for (int j = 0; j < 8; ++j) {
;         const int k0 = 16 * j + 4 * fq;
;         const float* src = (j < 4 ? ap->in[16] : ap->in[17]) + ((size_t)(l * 32 + g) * 16 + fr) * 64 + (j < 4 ? k0 : k0 - 64);
;         const f32x4 c4 = *(const f32x4*)src;
; #pragma unroll
;         for (int r = 0; r < 4; ++r) cmB[4 * j + r] = (j < 4) ? c4[r] : -c4[r];
;     }
;     const float dsk = ap->in[18][l * 512 + g * 16 + fr];
;     float tr = abr, ti = abi;
; #pragma unroll
;     for (int k = 0; k < 7; ++k) { const float nr = tr * tr - ti * ti, ni = 2.f * tr * ti; tr = nr; ti = ni; }
.LBB0_141:
	s_bfe_u32 s16, s9, 0x50006
	v_lshlrev_b32_e32 v0, 2, v79
	v_readlane_b32 s0, v254, 18
	v_lshl_or_b32 v0, s16, 10, v0
	v_readlane_b32 s1, v254, 19
	v_mov_b32_e32 v87, v1
	v_mov_b32_e32 v89, v1
	s_nop 2
	global_load_dwordx4 v[2:5], v0, s[0:1]
	s_or_b32 s0, s16, s8
	s_ashr_i32 s1, s0, 31
	s_lshl_b64 s[2:3], s[0:1], 12
	s_waitcnt vmcnt(12)
	v_lshl_or_b32 v22, v76, 2, s2
	v_mov_b32_e32 v23, s3
	s_waitcnt lgkmcnt(0)
	v_lshl_add_u64 v[18:19], s[6:7], 0, v[22:23]
	global_load_dwordx4 v[6:9], v[18:19], off
	global_load_dwordx4 v[10:13], v[18:19], off offset:16
	global_load_dwordx4 v[14:17], v[18:19], off offset:32
	s_nop 0
	global_load_dwordx4 v[18:21], v[18:19], off offset:48
	s_waitcnt vmcnt(13)
	v_lshl_add_u64 v[34:35], s[4:5], 0, v[22:23]
	global_load_dwordx4 v[22:25], v[34:35], off
	global_load_dwordx4 v[26:29], v[34:35], off offset:16
	global_load_dwordx4 v[30:33], v[34:35], off offset:32
	s_nop 0
	global_load_dwordx4 v[34:37], v[34:35], off offset:48
	s_and_b32 s0, s9, 0xffffffc0
	s_ashr_i32 s1, s0, 31
	s_lshl_b64 s[0:1], s[0:1], 9
	s_waitcnt vmcnt(7)
	v_mul_f32_e32 v0, v5, v6
	v_mul_f32_e32 v6, v4, v6
	v_mul_f32_e32 v38, v5, v7
	v_mul_f32_e32 v7, v4, v7
	v_mul_f32_e32 v39, v5, v8
	v_mul_f32_e32 v8, v4, v8
	v_mul_f32_e32 v40, v5, v9
	v_mul_f32_e32 v9, v4, v9
	s_waitcnt vmcnt(6)
	v_mul_f32_e32 v41, v5, v10
	v_mul_f32_e32 v10, v4, v10
	v_mul_f32_e32 v42, v5, v11
	v_mul_f32_e32 v11, v4, v11
	v_mul_f32_e32 v43, v5, v12
	v_mul_f32_e32 v12, v4, v12
	v_mul_f32_e32 v44, v5, v13
	v_mul_f32_e32 v13, v4, v13
	s_waitcnt vmcnt(5)
	v_mul_f32_e32 v45, v5, v14
	v_mul_f32_e32 v14, v4, v14
	v_mul_f32_e32 v46, v5, v15
	v_mul_f32_e32 v15, v4, v15
	v_mul_f32_e32 v47, v5, v16
	v_mul_f32_e32 v16, v4, v16
	v_mul_f32_e32 v48, v5, v17
	v_mul_f32_e32 v17, v4, v17
	s_waitcnt vmcnt(4)
	v_mul_f32_e32 v49, v5, v18
	v_mul_f32_e32 v18, v4, v18
	v_mul_f32_e32 v50, v5, v19
	v_mul_f32_e32 v19, v4, v19
	v_mul_f32_e32 v51, v5, v20
	v_mul_f32_e32 v20, v4, v20
	v_mul_f32_e32 v52, v5, v21
	v_mul_f32_e32 v21, v4, v21
	s_waitcnt vmcnt(3)
	v_fma_f32 v0, v4, v22, -v0
	v_fmac_f32_e32 v6, v5, v22
	v_fma_f32 v22, v4, v23, -v38
	v_fmac_f32_e32 v7, v5, v23
	v_fma_f32 v23, v4, v24, -v39
	v_fmac_f32_e32 v8, v5, v24
	v_fma_f32 v24, v4, v25, -v40
	v_fmac_f32_e32 v9, v5, v25
	s_waitcnt vmcnt(2)
	v_fma_f32 v25, v4, v26, -v41
	v_fmac_f32_e32 v10, v5, v26
	v_fma_f32 v26, v4, v27, -v42
	v_fmac_f32_e32 v11, v5, v27
	v_fma_f32 v27, v4, v28, -v43
	v_fmac_f32_e32 v12, v5, v28
	v_fma_f32 v28, v4, v29, -v44
	v_fmac_f32_e32 v13, v5, v29
	s_waitcnt vmcnt(1)
	v_fma_f32 v29, v4, v30, -v45
	v_fmac_f32_e32 v14, v5, v30
	v_fma_f32 v30, v4, v31, -v46
	v_fmac_f32_e32 v15, v5, v31
	v_fma_f32 v31, v4, v32, -v47
	v_fmac_f32_e32 v16, v5, v32
	v_fma_f32 v32, v4, v33, -v48
	v_fmac_f32_e32 v17, v5, v33
	s_waitcnt vmcnt(0)
	v_fma_f32 v33, v4, v34, -v49
	v_fmac_f32_e32 v18, v5, v34
	v_fma_f32 v34, v4, v35, -v50
	v_fmac_f32_e32 v19, v5, v35
	v_fma_f32 v35, v4, v36, -v51
	v_fmac_f32_e32 v20, v5, v36
	v_fma_f32 v4, v4, v37, -v52
	v_fmac_f32_e32 v21, v5, v37
	v_cvt_pk_bf16_f32 v101, v0, v22
	v_cvt_pk_bf16_f32 v102, v6, v7
	v_cvt_pk_bf16_f32 v103, v23, v24
	v_cvt_pk_bf16_f32 v104, v8, v9
	v_cvt_pk_bf16_f32 v105, v25, v26
	v_cvt_pk_bf16_f32 v106, v10, v11
	v_cvt_pk_bf16_f32 v107, v27, v28
	v_cvt_pk_bf16_f32 v108, v12, v13
	v_cvt_pk_bf16_f32 v109, v29, v30
	v_cvt_pk_bf16_f32 v110, v14, v15
	v_cvt_pk_bf16_f32 v111, v31, v32
	v_cvt_pk_bf16_f32 v112, v16, v17
	v_cvt_pk_bf16_f32 v113, v33, v34
	v_cvt_pk_bf16_f32 v114, v18, v19
	v_cvt_pk_bf16_f32 v115, v35, v4
	v_cvt_pk_bf16_f32 v116, v20, v21
	s_load_dwordx4 s[12:15], s[82:83], 0x80
	s_load_dwordx2 s[10:11], s[82:83], 0x90
	v_mul_f32_e32 v0, v3, v3
	v_fma_f32 v0, v2, v2, -v0
	s_waitcnt lgkmcnt(0)
	s_add_u32 s12, s12, s2
	s_addc_u32 s13, s13, s3
	s_add_u32 s2, s14, s2
	s_addc_u32 s3, s15, s3
	v_lshl_add_u64 v[4:5], s[12:13], 0, v[86:87]
	v_lshl_add_u64 v[20:21], s[2:3], 0, v[86:87]
	v_lshl_add_u64 v[16:17], v[4:5], 0, v[88:89]
	v_lshl_add_u64 v[20:21], v[20:21], 0, v[88:89]
	s_lshl_b32 s2, s16, 4
	global_load_dwordx4 v[4:7], v[16:17], off
	global_load_dwordx4 v[8:11], v[16:17], off offset:64
	global_load_dwordx4 v[12:15], v[16:17], off offset:128
	s_nop 0
	global_load_dwordx4 v[16:19], v[16:17], off offset:192
	s_nop 0
	global_load_dwordx4 v[64:67], v[20:21], off
	global_load_dwordx4 v[60:63], v[20:21], off offset:64
	global_load_dwordx4 v[56:59], v[20:21], off offset:128
	global_load_dwordx4 v[52:55], v[20:21], off offset:192
	v_or_b32_e32 v20, s2, v98
	v_ashrrev_i32_e32 v21, 31, v20
	v_lshl_add_u64 v[20:21], v[20:21], 2, s[10:11]
	global_load_dword v87, v[20:21], off
	v_add_f32_e32 v20, v2, v2
	v_mul_f32_e32 v20, v3, v20
	v_mul_f32_e32 v21, v20, v20
	v_fma_f32 v21, v0, v0, -v21
	v_add_f32_e32 v0, v0, v0
	v_mul_f32_e32 v0, v20, v0
	v_mul_f32_e32 v20, v0, v0
	v_fma_f32 v20, v21, v21, -v20
	v_add_f32_e32 v21, v21, v21
	v_mul_f32_e32 v0, v0, v21
	v_mul_f32_e32 v21, v0, v0
	v_fma_f32 v21, v20, v20, -v21
	v_add_f32_e32 v20, v20, v20
	v_mul_f32_e32 v0, v0, v20
	v_mul_f32_e32 v20, v0, v0
	v_fma_f32 v20, v21, v21, -v20
	v_add_f32_e32 v21, v21, v21
	v_mul_f32_e32 v0, v0, v21
	v_mul_f32_e32 v21, v0, v0
	v_fma_f32 v21, v20, v20, -v21
	v_add_f32_e32 v20, v20, v20
	v_mul_f32_e32 v0, v0, v20
	v_mul_f32_e32 v20, v0, v0
	v_fma_f32 v20, v21, v21, -v20
	v_add_f32_e32 v21, v21, v21
	s_and_b32 s3, s9, 63
	s_cmp_lt_u32 s3, 8
	v_mul_f32_e32 v22, v0, v21
	s_branch .Lp3_carry
; __device__ __forceinline__ void ssm_pass3h(CArgs* ap, const float* COEF, int l, const bf16_t* PROJ, const float* SST, bf16_t* YS, LAS unsigned char* wlds, int unit, int lane) {
;     ...
;     float hr = 0.f, hi = 0.f;
;     const float* sp = SST + ((size_t)(unit - c) * 64 + lane) * 2;
;     int cc = 0;
;     for (; cc + 8 <= c; cc += 8) {
;         float2 s8[8];
; #pragma unroll
;         for (int j = 0; j < 8; ++j) s8[j] = *(const float2*)(sp + (size_t)(cc + j) * 128);
; #pragma unroll
;         for (int j = 0; j < 8; ++j) { const float nr = tr * hr - ti * hi + s8[j].x, ni = tr * hi + ti * hr + s8[j].y; hr = nr; hi = ni; }
;     }
;     for (; cc < c; ++cc) { const float2 s = *(const float2*)(sp + (size_t)cc * 128); const float nr = tr * hr - ti * hi + s.x, ni = tr * hi + ti * hr + s.y; hr = nr; hi = ni; }
.Lp3_carry:
	v_mov_b32_e32 v90, 0
	v_mov_b32_e32 v91, 0
	s_cmp_eq_u32 s3, 0
	s_cbranch_scc1 .LBB0_148
	v_mov_b32_e32 v21, v20
	v_mov_b32_e32 v23, v22
	v_lshl_add_u64 v[24:25], v[84:85], 0, s[0:1]
	s_mov_b64 s[12:13], 0x1000
	s_mov_b32 s78, 0
	v_lshl_add_u64 v[28:29], v[24:25], 0, s[12:13]
	global_load_dwordx2 v[168:169], v[24:25], off
	global_load_dwordx2 v[170:171], v[24:25], off offset:512
	global_load_dwordx2 v[172:173], v[24:25], off offset:1024
	global_load_dwordx2 v[174:175], v[24:25], off offset:1536
	global_load_dwordx2 v[176:177], v[24:25], off offset:2048
	global_load_dwordx2 v[178:179], v[24:25], off offset:2560
	global_load_dwordx2 v[180:181], v[24:25], off offset:3072
	global_load_dwordx2 v[182:183], v[24:25], off offset:3584
	global_load_dwordx2 v[184:185], v[28:29], off
	global_load_dwordx2 v[186:187], v[28:29], off offset:512
	global_load_dwordx2 v[188:189], v[28:29], off offset:1024
	global_load_dwordx2 v[190:191], v[28:29], off offset:1536
	global_load_dwordx2 v[144:145], v[28:29], off offset:2048
	global_load_dwordx2 v[146:147], v[28:29], off offset:2560
	global_load_dwordx2 v[148:149], v[28:29], off offset:3072
	global_load_dwordx2 v[150:151], v[28:29], off offset:3584
	v_lshl_add_u64 v[24:25], v[28:29], 0, s[12:13]
	v_lshl_add_u64 v[28:29], v[24:25], 0, s[12:13]
.Lp3_top:
	global_load_dwordx2 v[208:209], v[24:25], off
	global_load_dwordx2 v[210:211], v[24:25], off offset:512
	global_load_dwordx2 v[212:213], v[24:25], off offset:1024
	global_load_dwordx2 v[214:215], v[24:25], off offset:1536
	global_load_dwordx2 v[216:217], v[24:25], off offset:2048
	global_load_dwordx2 v[218:219], v[24:25], off offset:2560
	global_load_dwordx2 v[220:221], v[24:25], off offset:3072
	global_load_dwordx2 v[222:223], v[24:25], off offset:3584
	global_load_dwordx2 v[224:225], v[28:29], off
	global_load_dwordx2 v[226:227], v[28:29], off offset:512
	global_load_dwordx2 v[228:229], v[28:29], off offset:1024
	global_load_dwordx2 v[230:231], v[28:29], off offset:1536
	global_load_dwordx2 v[232:233], v[28:29], off offset:2048
	global_load_dwordx2 v[234:235], v[28:29], off offset:2560
	global_load_dwordx2 v[236:237], v[28:29], off offset:3072
	global_load_dwordx2 v[238:239], v[28:29], off offset:3584
	v_lshl_add_u64 v[24:25], v[28:29], 0, s[12:13]
	v_lshl_add_u64 v[28:29], v[24:25], 0, s[12:13]
	s_cmp_ge_u32 s78, s3
	s_cbranch_scc1 .Lp3_done
	v_pk_mul_f32 v[26:27], v[22:23], v[90:91]
	s_nop 0
	v_pk_fma_f32 v[34:35], v[20:21], v[90:91], v[26:27] op_sel:[0,0,1] op_sel_hi:[1,1,0] neg_lo:[0,0,1] neg_hi:[0,0,1]
	v_pk_fma_f32 v[26:27], v[20:21], v[90:91], v[26:27] op_sel:[0,0,1] op_sel_hi:[1,1,0]
	s_nop 0
	v_mov_b32_e32 v35, v27
	s_waitcnt vmcnt(31)
	v_pk_add_f32 v[90:91], v[34:35], v[168:169]
	s_add_i32 s78, s78, 1
	s_nop 0
	s_cmp_ge_u32 s78, s3
	s_cbranch_scc1 .Lp3_done
	v_pk_mul_f32 v[26:27], v[22:23], v[90:91]
	s_nop 0
	v_pk_fma_f32 v[34:35], v[20:21], v[90:91], v[26:27] op_sel:[0,0,1] op_sel_hi:[1,1,0] neg_lo:[0,0,1] neg_hi:[0,0,1]
	v_pk_fma_f32 v[26:27], v[20:21], v[90:91], v[26:27] op_sel:[0,0,1] op_sel_hi:[1,1,0]
	s_nop 0
	v_mov_b32_e32 v35, v27
	s_waitcnt vmcnt(30)
	v_pk_add_f32 v[90:91], v[34:35], v[170:171]
	s_add_i32 s78, s78, 1
	s_nop 0
	s_cmp_ge_u32 s78, s3
	s_cbranch_scc1 .Lp3_done
	v_pk_mul_f32 v[26:27], v[22:23], v[90:91]
	s_nop 0
	v_pk_fma_f32 v[34:35], v[20:21], v[90:91], v[26:27] op_sel:[0,0,1] op_sel_hi:[1,1,0] neg_lo:[0,0,1] neg_hi:[0,0,1]
	v_pk_fma_f32 v[26:27], v[20:21], v[90:91], v[26:27] op_sel:[0,0,1] op_sel_hi:[1,1,0]
	s_nop 0
	v_mov_b32_e32 v35, v27
	s_waitcnt vmcnt(29)
	v_pk_add_f32 v[90:91], v[34:35], v[172:173]
	s_add_i32 s78, s78, 1
	s_nop 0
	s_cmp_ge_u32 s78, s3
	s_cbranch_scc1 .Lp3_done
	v_pk_mul_f32 v[26:27], v[22:23], v[90:91]
	s_nop 0
	v_pk_fma_f32 v[34:35], v[20:21], v[90:91], v[26:27] op_sel:[0,0,1] op_sel_hi:[1,1,0] neg_lo:[0,0,1] neg_hi:[0,0,1]
	v_pk_fma_f32 v[26:27], v[20:21], v[90:91], v[26:27] op_sel:[0,0,1] op_sel_hi:[1,1,0]
	s_nop 0
	v_mov_b32_e32 v35, v27
	s_waitcnt vmcnt(28)
	v_pk_add_f32 v[90:91], v[34:35], v[174:175]
	s_add_i32 s78, s78, 1
	s_nop 0
	s_cmp_ge_u32 s78, s3
	s_cbranch_scc1 .Lp3_done
	v_pk_mul_f32 v[26:27], v[22:23], v[90:91]
	s_nop 0
	v_pk_fma_f32 v[34:35], v[20:21], v[90:91], v[26:27] op_sel:[0,0,1] op_sel_hi:[1,1,0] neg_lo:[0,0,1] neg_hi:[0,0,1]
	v_pk_fma_f32 v[26:27], v[20:21], v[90:91], v[26:27] op_sel:[0,0,1] op_sel_hi:[1,1,0]
	s_nop 0
	v_mov_b32_e32 v35, v27
	s_waitcnt vmcnt(27)
	v_pk_add_f32 v[90:91], v[34:35], v[176:177]
	s_add_i32 s78, s78, 1
	s_nop 0
	s_cmp_ge_u32 s78, s3
	s_cbranch_scc1 .Lp3_done
	v_pk_mul_f32 v[26:27], v[22:23], v[90:91]
	s_nop 0
	v_pk_fma_f32 v[34:35], v[20:21], v[90:91], v[26:27] op_sel:[0,0,1] op_sel_hi:[1,1,0] neg_lo:[0,0,1] neg_hi:[0,0,1]
	v_pk_fma_f32 v[26:27], v[20:21], v[90:91], v[26:27] op_sel:[0,0,1] op_sel_hi:[1,1,0]
	s_nop 0
	v_mov_b32_e32 v35, v27
	s_waitcnt vmcnt(26)
	v_pk_add_f32 v[90:91], v[34:35], v[178:179]
	s_add_i32 s78, s78, 1
	s_nop 0
	s_cmp_ge_u32 s78, s3
	s_cbranch_scc1 .Lp3_done
	v_pk_mul_f32 v[26:27], v[22:23], v[90:91]
	s_nop 0
	v_pk_fma_f32 v[34:35], v[20:21], v[90:91], v[26:27] op_sel:[0,0,1] op_sel_hi:[1,1,0] neg_lo:[0,0,1] neg_hi:[0,0,1]
	v_pk_fma_f32 v[26:27], v[20:21], v[90:91], v[26:27] op_sel:[0,0,1] op_sel_hi:[1,1,0]
	s_nop 0
	v_mov_b32_e32 v35, v27
	s_waitcnt vmcnt(25)
	v_pk_add_f32 v[90:91], v[34:35], v[180:181]
	s_add_i32 s78, s78, 1
	s_nop 0
	s_cmp_ge_u32 s78, s3
	s_cbranch_scc1 .Lp3_done
	v_pk_mul_f32 v[26:27], v[22:23], v[90:91]
	s_nop 0
	v_pk_fma_f32 v[34:35], v[20:21], v[90:91], v[26:27] op_sel:[0,0,1] op_sel_hi:[1,1,0] neg_lo:[0,0,1] neg_hi:[0,0,1]
	v_pk_fma_f32 v[26:27], v[20:21], v[90:91], v[26:27] op_sel:[0,0,1] op_sel_hi:[1,1,0]
	s_nop 0
	v_mov_b32_e32 v35, v27
	s_waitcnt vmcnt(24)
	v_pk_add_f32 v[90:91], v[34:35], v[182:183]
	s_add_i32 s78, s78, 1
	s_nop 0
	s_cmp_ge_u32 s78, s3
	s_cbranch_scc1 .Lp3_done
; __device__ __forceinline__ void ssm_pass3h(CArgs* ap, const float* COEF, int l, const bf16_t* PROJ, const float* SST, bf16_t* YS, LAS unsigned char* wlds, int unit, int lane) {
;     ...
;     float hr = 0.f, hi = 0.f;
;     const float* sp = SST + ((size_t)(unit - c) * 64 + lane) * 2;
;     int cc = 0;
;     for (; cc + 8 <= c; cc += 8) {
;         float2 s8[8];
; #pragma unroll
;         for (int j = 0; j < 8; ++j) s8[j] = *(const float2*)(sp + (size_t)(cc + j) * 128);
; #pragma unroll
;         for (int j = 0; j < 8; ++j) { const float nr = tr * hr - ti * hi + s8[j].x, ni = tr * hi + ti * hr + s8[j].y; hr = nr; hi = ni; }
;     }
;     for (; cc < c; ++cc) { const float2 s = *(const float2*)(sp + (size_t)cc * 128); const float nr = tr * hr - ti * hi + s.x, ni = tr * hi + ti * hr + s.y; hr = nr; hi = ni; }
	v_pk_mul_f32 v[26:27], v[22:23], v[90:91]
	s_nop 0
	v_pk_fma_f32 v[34:35], v[20:21], v[90:91], v[26:27] op_sel:[0,0,1] op_sel_hi:[1,1,0] neg_lo:[0,0,1] neg_hi:[0,0,1]
	v_pk_fma_f32 v[26:27], v[20:21], v[90:91], v[26:27] op_sel:[0,0,1] op_sel_hi:[1,1,0]
	s_nop 0
	v_mov_b32_e32 v35, v27
	s_waitcnt vmcnt(23)
	v_pk_add_f32 v[90:91], v[34:35], v[184:185]
	s_add_i32 s78, s78, 1
	s_nop 0
	s_cmp_ge_u32 s78, s3
	s_cbranch_scc1 .Lp3_done
	v_pk_mul_f32 v[26:27], v[22:23], v[90:91]
	s_nop 0
	v_pk_fma_f32 v[34:35], v[20:21], v[90:91], v[26:27] op_sel:[0,0,1] op_sel_hi:[1,1,0] neg_lo:[0,0,1] neg_hi:[0,0,1]
	v_pk_fma_f32 v[26:27], v[20:21], v[90:91], v[26:27] op_sel:[0,0,1] op_sel_hi:[1,1,0]
	s_nop 0
	v_mov_b32_e32 v35, v27
	s_waitcnt vmcnt(22)
	v_pk_add_f32 v[90:91], v[34:35], v[186:187]
	s_add_i32 s78, s78, 1
	s_nop 0
	s_cmp_ge_u32 s78, s3
	s_cbranch_scc1 .Lp3_done
	v_pk_mul_f32 v[26:27], v[22:23], v[90:91]
	s_nop 0
	v_pk_fma_f32 v[34:35], v[20:21], v[90:91], v[26:27] op_sel:[0,0,1] op_sel_hi:[1,1,0] neg_lo:[0,0,1] neg_hi:[0,0,1]
	v_pk_fma_f32 v[26:27], v[20:21], v[90:91], v[26:27] op_sel:[0,0,1] op_sel_hi:[1,1,0]
	s_nop 0
	v_mov_b32_e32 v35, v27
	s_waitcnt vmcnt(21)
	v_pk_add_f32 v[90:91], v[34:35], v[188:189]
	s_add_i32 s78, s78, 1
	s_nop 0
	s_cmp_ge_u32 s78, s3
	s_cbranch_scc1 .Lp3_done
	v_pk_mul_f32 v[26:27], v[22:23], v[90:91]
	s_nop 0
	v_pk_fma_f32 v[34:35], v[20:21], v[90:91], v[26:27] op_sel:[0,0,1] op_sel_hi:[1,1,0] neg_lo:[0,0,1] neg_hi:[0,0,1]
	v_pk_fma_f32 v[26:27], v[20:21], v[90:91], v[26:27] op_sel:[0,0,1] op_sel_hi:[1,1,0]
	s_nop 0
	v_mov_b32_e32 v35, v27
	s_waitcnt vmcnt(20)
	v_pk_add_f32 v[90:91], v[34:35], v[190:191]
	s_add_i32 s78, s78, 1
	s_nop 0
	s_cmp_ge_u32 s78, s3
	s_cbranch_scc1 .Lp3_done
	v_pk_mul_f32 v[26:27], v[22:23], v[90:91]
	s_nop 0
	v_pk_fma_f32 v[34:35], v[20:21], v[90:91], v[26:27] op_sel:[0,0,1] op_sel_hi:[1,1,0] neg_lo:[0,0,1] neg_hi:[0,0,1]
	v_pk_fma_f32 v[26:27], v[20:21], v[90:91], v[26:27] op_sel:[0,0,1] op_sel_hi:[1,1,0]
	s_nop 0
	v_mov_b32_e32 v35, v27
	s_waitcnt vmcnt(19)
	v_pk_add_f32 v[90:91], v[34:35], v[144:145]
	s_add_i32 s78, s78, 1
	s_nop 0
	s_cmp_ge_u32 s78, s3
	s_cbranch_scc1 .Lp3_done
	v_pk_mul_f32 v[26:27], v[22:23], v[90:91]
	s_nop 0
	v_pk_fma_f32 v[34:35], v[20:21], v[90:91], v[26:27] op_sel:[0,0,1] op_sel_hi:[1,1,0] neg_lo:[0,0,1] neg_hi:[0,0,1]
	v_pk_fma_f32 v[26:27], v[20:21], v[90:91], v[26:27] op_sel:[0,0,1] op_sel_hi:[1,1,0]
	s_nop 0
	v_mov_b32_e32 v35, v27
	s_waitcnt vmcnt(18)
	v_pk_add_f32 v[90:91], v[34:35], v[146:147]
	s_add_i32 s78, s78, 1
	s_nop 0
	s_cmp_ge_u32 s78, s3
	s_cbranch_scc1 .Lp3_done
	v_pk_mul_f32 v[26:27], v[22:23], v[90:91]
	s_nop 0
	v_pk_fma_f32 v[34:35], v[20:21], v[90:91], v[26:27] op_sel:[0,0,1] op_sel_hi:[1,1,0] neg_lo:[0,0,1] neg_hi:[0,0,1]
	v_pk_fma_f32 v[26:27], v[20:21], v[90:91], v[26:27] op_sel:[0,0,1] op_sel_hi:[1,1,0]
	s_nop 0
	v_mov_b32_e32 v35, v27
	s_waitcnt vmcnt(17)
	v_pk_add_f32 v[90:91], v[34:35], v[148:149]
	s_add_i32 s78, s78, 1
	s_nop 0
	s_cmp_ge_u32 s78, s3
	s_cbranch_scc1 .Lp3_done
	v_pk_mul_f32 v[26:27], v[22:23], v[90:91]
	s_nop 0
	v_pk_fma_f32 v[34:35], v[20:21], v[90:91], v[26:27] op_sel:[0,0,1] op_sel_hi:[1,1,0] neg_lo:[0,0,1] neg_hi:[0,0,1]
	v_pk_fma_f32 v[26:27], v[20:21], v[90:91], v[26:27] op_sel:[0,0,1] op_sel_hi:[1,1,0]
	s_nop 0
	v_mov_b32_e32 v35, v27
	s_waitcnt vmcnt(16)
	v_pk_add_f32 v[90:91], v[34:35], v[150:151]
	s_add_i32 s78, s78, 1
	s_nop 0
	global_load_dwordx2 v[168:169], v[24:25], off
	global_load_dwordx2 v[170:171], v[24:25], off offset:512
	global_load_dwordx2 v[172:173], v[24:25], off offset:1024
	global_load_dwordx2 v[174:175], v[24:25], off offset:1536
	global_load_dwordx2 v[176:177], v[24:25], off offset:2048
	global_load_dwordx2 v[178:179], v[24:25], off offset:2560
	global_load_dwordx2 v[180:181], v[24:25], off offset:3072
	global_load_dwordx2 v[182:183], v[24:25], off offset:3584
	global_load_dwordx2 v[184:185], v[28:29], off
	global_load_dwordx2 v[186:187], v[28:29], off offset:512
	global_load_dwordx2 v[188:189], v[28:29], off offset:1024
	global_load_dwordx2 v[190:191], v[28:29], off offset:1536
	global_load_dwordx2 v[144:145], v[28:29], off offset:2048
	global_load_dwordx2 v[146:147], v[28:29], off offset:2560
	global_load_dwordx2 v[148:149], v[28:29], off offset:3072
	global_load_dwordx2 v[150:151], v[28:29], off offset:3584
	v_lshl_add_u64 v[24:25], v[28:29], 0, s[12:13]
	v_lshl_add_u64 v[28:29], v[24:25], 0, s[12:13]
	s_cmp_ge_u32 s78, s3
	s_cbranch_scc1 .Lp3_done
	v_pk_mul_f32 v[26:27], v[22:23], v[90:91]
	s_nop 0
	v_pk_fma_f32 v[34:35], v[20:21], v[90:91], v[26:27] op_sel:[0,0,1] op_sel_hi:[1,1,0] neg_lo:[0,0,1] neg_hi:[0,0,1]
	v_pk_fma_f32 v[26:27], v[20:21], v[90:91], v[26:27] op_sel:[0,0,1] op_sel_hi:[1,1,0]
	s_nop 0
	v_mov_b32_e32 v35, v27
	s_waitcnt vmcnt(31)
	v_pk_add_f32 v[90:91], v[34:35], v[208:209]
	s_add_i32 s78, s78, 1
	s_nop 0
	s_cmp_ge_u32 s78, s3
	s_cbranch_scc1 .Lp3_done
	v_pk_mul_f32 v[26:27], v[22:23], v[90:91]
	s_nop 0
	v_pk_fma_f32 v[34:35], v[20:21], v[90:91], v[26:27] op_sel:[0,0,1] op_sel_hi:[1,1,0] neg_lo:[0,0,1] neg_hi:[0,0,1]
	v_pk_fma_f32 v[26:27], v[20:21], v[90:91], v[26:27] op_sel:[0,0,1] op_sel_hi:[1,1,0]
	s_nop 0
	v_mov_b32_e32 v35, v27
	s_waitcnt vmcnt(30)
	v_pk_add_f32 v[90:91], v[34:35], v[210:211]
	s_add_i32 s78, s78, 1
	s_nop 0
	s_cmp_ge_u32 s78, s3
	s_cbranch_scc1 .Lp3_done
	v_pk_mul_f32 v[26:27], v[22:23], v[90:91]
	s_nop 0
	v_pk_fma_f32 v[34:35], v[20:21], v[90:91], v[26:27] op_sel:[0,0,1] op_sel_hi:[1,1,0] neg_lo:[0,0,1] neg_hi:[0,0,1]
	v_pk_fma_f32 v[26:27], v[20:21], v[90:91], v[26:27] op_sel:[0,0,1] op_sel_hi:[1,1,0]
	s_nop 0
	v_mov_b32_e32 v35, v27
	s_waitcnt vmcnt(29)
	v_pk_add_f32 v[90:91], v[34:35], v[212:213]
	s_add_i32 s78, s78, 1
	s_nop 0
	s_cmp_ge_u32 s78, s3
	s_cbranch_scc1 .Lp3_done
; __device__ __forceinline__ void ssm_pass3h(CArgs* ap, const float* COEF, int l, const bf16_t* PROJ, const float* SST, bf16_t* YS, LAS unsigned char* wlds, int unit, int lane) {
;     ...
;     float hr = 0.f, hi = 0.f;
;     const float* sp = SST + ((size_t)(unit - c) * 64 + lane) * 2;
;     int cc = 0;
;     for (; cc + 8 <= c; cc += 8) {
;         float2 s8[8];
; #pragma unroll
;         for (int j = 0; j < 8; ++j) s8[j] = *(const float2*)(sp + (size_t)(cc + j) * 128);
; #pragma unroll
;         for (int j = 0; j < 8; ++j) { const float nr = tr * hr - ti * hi + s8[j].x, ni = tr * hi + ti * hr + s8[j].y; hr = nr; hi = ni; }
;     }
;     for (; cc < c; ++cc) { const float2 s = *(const float2*)(sp + (size_t)cc * 128); const float nr = tr * hr - ti * hi + s.x, ni = tr * hi + ti * hr + s.y; hr = nr; hi = ni; }
	v_pk_mul_f32 v[26:27], v[22:23], v[90:91]
	s_nop 0
	v_pk_fma_f32 v[34:35], v[20:21], v[90:91], v[26:27] op_sel:[0,0,1] op_sel_hi:[1,1,0] neg_lo:[0,0,1] neg_hi:[0,0,1]
	v_pk_fma_f32 v[26:27], v[20:21], v[90:91], v[26:27] op_sel:[0,0,1] op_sel_hi:[1,1,0]
	s_nop 0
	v_mov_b32_e32 v35, v27
	s_waitcnt vmcnt(28)
	v_pk_add_f32 v[90:91], v[34:35], v[214:215]
	s_add_i32 s78, s78, 1
	s_nop 0
	s_cmp_ge_u32 s78, s3
	s_cbranch_scc1 .Lp3_done
	v_pk_mul_f32 v[26:27], v[22:23], v[90:91]
	s_nop 0
	v_pk_fma_f32 v[34:35], v[20:21], v[90:91], v[26:27] op_sel:[0,0,1] op_sel_hi:[1,1,0] neg_lo:[0,0,1] neg_hi:[0,0,1]
	v_pk_fma_f32 v[26:27], v[20:21], v[90:91], v[26:27] op_sel:[0,0,1] op_sel_hi:[1,1,0]
	s_nop 0
	v_mov_b32_e32 v35, v27
	s_waitcnt vmcnt(27)
	v_pk_add_f32 v[90:91], v[34:35], v[216:217]
	s_add_i32 s78, s78, 1
	s_nop 0
	s_cmp_ge_u32 s78, s3
	s_cbranch_scc1 .Lp3_done
	v_pk_mul_f32 v[26:27], v[22:23], v[90:91]
	s_nop 0
	v_pk_fma_f32 v[34:35], v[20:21], v[90:91], v[26:27] op_sel:[0,0,1] op_sel_hi:[1,1,0] neg_lo:[0,0,1] neg_hi:[0,0,1]
	v_pk_fma_f32 v[26:27], v[20:21], v[90:91], v[26:27] op_sel:[0,0,1] op_sel_hi:[1,1,0]
	s_nop 0
	v_mov_b32_e32 v35, v27
	s_waitcnt vmcnt(26)
	v_pk_add_f32 v[90:91], v[34:35], v[218:219]
	s_add_i32 s78, s78, 1
	s_nop 0
	s_cmp_ge_u32 s78, s3
	s_cbranch_scc1 .Lp3_done
	v_pk_mul_f32 v[26:27], v[22:23], v[90:91]
	s_nop 0
	v_pk_fma_f32 v[34:35], v[20:21], v[90:91], v[26:27] op_sel:[0,0,1] op_sel_hi:[1,1,0] neg_lo:[0,0,1] neg_hi:[0,0,1]
	v_pk_fma_f32 v[26:27], v[20:21], v[90:91], v[26:27] op_sel:[0,0,1] op_sel_hi:[1,1,0]
	s_nop 0
	v_mov_b32_e32 v35, v27
	s_waitcnt vmcnt(25)
	v_pk_add_f32 v[90:91], v[34:35], v[220:221]
	s_add_i32 s78, s78, 1
	s_nop 0
	s_cmp_ge_u32 s78, s3
	s_cbranch_scc1 .Lp3_done
	v_pk_mul_f32 v[26:27], v[22:23], v[90:91]
	s_nop 0
	v_pk_fma_f32 v[34:35], v[20:21], v[90:91], v[26:27] op_sel:[0,0,1] op_sel_hi:[1,1,0] neg_lo:[0,0,1] neg_hi:[0,0,1]
	v_pk_fma_f32 v[26:27], v[20:21], v[90:91], v[26:27] op_sel:[0,0,1] op_sel_hi:[1,1,0]
	s_nop 0
	v_mov_b32_e32 v35, v27
	s_waitcnt vmcnt(24)
	v_pk_add_f32 v[90:91], v[34:35], v[222:223]
	s_add_i32 s78, s78, 1
	s_nop 0
	s_cmp_ge_u32 s78, s3
	s_cbranch_scc1 .Lp3_done
	v_pk_mul_f32 v[26:27], v[22:23], v[90:91]
	s_nop 0
	v_pk_fma_f32 v[34:35], v[20:21], v[90:91], v[26:27] op_sel:[0,0,1] op_sel_hi:[1,1,0] neg_lo:[0,0,1] neg_hi:[0,0,1]
	v_pk_fma_f32 v[26:27], v[20:21], v[90:91], v[26:27] op_sel:[0,0,1] op_sel_hi:[1,1,0]
	s_nop 0
	v_mov_b32_e32 v35, v27
	s_waitcnt vmcnt(23)
	v_pk_add_f32 v[90:91], v[34:35], v[224:225]
	s_add_i32 s78, s78, 1
	s_nop 0
	s_cmp_ge_u32 s78, s3
	s_cbranch_scc1 .Lp3_done
	v_pk_mul_f32 v[26:27], v[22:23], v[90:91]
	s_nop 0
	v_pk_fma_f32 v[34:35], v[20:21], v[90:91], v[26:27] op_sel:[0,0,1] op_sel_hi:[1,1,0] neg_lo:[0,0,1] neg_hi:[0,0,1]
	v_pk_fma_f32 v[26:27], v[20:21], v[90:91], v[26:27] op_sel:[0,0,1] op_sel_hi:[1,1,0]
	s_nop 0
	v_mov_b32_e32 v35, v27
	s_waitcnt vmcnt(22)
	v_pk_add_f32 v[90:91], v[34:35], v[226:227]
	s_add_i32 s78, s78, 1
	s_nop 0
	s_cmp_ge_u32 s78, s3
	s_cbranch_scc1 .Lp3_done
	v_pk_mul_f32 v[26:27], v[22:23], v[90:91]
	s_nop 0
	v_pk_fma_f32 v[34:35], v[20:21], v[90:91], v[26:27] op_sel:[0,0,1] op_sel_hi:[1,1,0] neg_lo:[0,0,1] neg_hi:[0,0,1]
	v_pk_fma_f32 v[26:27], v[20:21], v[90:91], v[26:27] op_sel:[0,0,1] op_sel_hi:[1,1,0]
	s_nop 0
	v_mov_b32_e32 v35, v27
	s_waitcnt vmcnt(21)
	v_pk_add_f32 v[90:91], v[34:35], v[228:229]
	s_add_i32 s78, s78, 1
	s_nop 0
	s_cmp_ge_u32 s78, s3
	s_cbranch_scc1 .Lp3_done
	v_pk_mul_f32 v[26:27], v[22:23], v[90:91]
	s_nop 0
	v_pk_fma_f32 v[34:35], v[20:21], v[90:91], v[26:27] op_sel:[0,0,1] op_sel_hi:[1,1,0] neg_lo:[0,0,1] neg_hi:[0,0,1]
	v_pk_fma_f32 v[26:27], v[20:21], v[90:91], v[26:27] op_sel:[0,0,1] op_sel_hi:[1,1,0]
	s_nop 0
	v_mov_b32_e32 v35, v27
	s_waitcnt vmcnt(20)
	v_pk_add_f32 v[90:91], v[34:35], v[230:231]
	s_add_i32 s78, s78, 1
	s_nop 0
	s_cmp_ge_u32 s78, s3
	s_cbranch_scc1 .Lp3_done
	v_pk_mul_f32 v[26:27], v[22:23], v[90:91]
	s_nop 0
	v_pk_fma_f32 v[34:35], v[20:21], v[90:91], v[26:27] op_sel:[0,0,1] op_sel_hi:[1,1,0] neg_lo:[0,0,1] neg_hi:[0,0,1]
	v_pk_fma_f32 v[26:27], v[20:21], v[90:91], v[26:27] op_sel:[0,0,1] op_sel_hi:[1,1,0]
	s_nop 0
	v_mov_b32_e32 v35, v27
	s_waitcnt vmcnt(19)
	v_pk_add_f32 v[90:91], v[34:35], v[232:233]
	s_add_i32 s78, s78, 1
	s_nop 0
	s_cmp_ge_u32 s78, s3
	s_cbranch_scc1 .Lp3_done
	v_pk_mul_f32 v[26:27], v[22:23], v[90:91]
	s_nop 0
	v_pk_fma_f32 v[34:35], v[20:21], v[90:91], v[26:27] op_sel:[0,0,1] op_sel_hi:[1,1,0] neg_lo:[0,0,1] neg_hi:[0,0,1]
	v_pk_fma_f32 v[26:27], v[20:21], v[90:91], v[26:27] op_sel:[0,0,1] op_sel_hi:[1,1,0]
	s_nop 0
	v_mov_b32_e32 v35, v27
	s_waitcnt vmcnt(18)
	v_pk_add_f32 v[90:91], v[34:35], v[234:235]
	s_add_i32 s78, s78, 1
	s_nop 0
	s_cmp_ge_u32 s78, s3
	s_cbranch_scc1 .Lp3_done
	v_pk_mul_f32 v[26:27], v[22:23], v[90:91]
	s_nop 0
	v_pk_fma_f32 v[34:35], v[20:21], v[90:91], v[26:27] op_sel:[0,0,1] op_sel_hi:[1,1,0] neg_lo:[0,0,1] neg_hi:[0,0,1]
	v_pk_fma_f32 v[26:27], v[20:21], v[90:91], v[26:27] op_sel:[0,0,1] op_sel_hi:[1,1,0]
	s_nop 0
	v_mov_b32_e32 v35, v27
	s_waitcnt vmcnt(17)
	v_pk_add_f32 v[90:91], v[34:35], v[236:237]
	s_add_i32 s78, s78, 1
	s_nop 0
	s_cmp_ge_u32 s78, s3
	s_cbranch_scc1 .Lp3_done
	v_pk_mul_f32 v[26:27], v[22:23], v[90:91]
	s_nop 0
	v_pk_fma_f32 v[34:35], v[20:21], v[90:91], v[26:27] op_sel:[0,0,1] op_sel_hi:[1,1,0] neg_lo:[0,0,1] neg_hi:[0,0,1]
	v_pk_fma_f32 v[26:27], v[20:21], v[90:91], v[26:27] op_sel:[0,0,1] op_sel_hi:[1,1,0]
	s_nop 0
	v_mov_b32_e32 v35, v27
	s_waitcnt vmcnt(16)
	v_pk_add_f32 v[90:91], v[34:35], v[238:239]
	s_add_i32 s78, s78, 1
	s_nop 0
	s_branch .Lp3_top
.Lp3_done:
	s_waitcnt vmcnt(0)
	s_branch .LBB0_148
	v_mov_b32_e32 v90, 0
	v_lshl_add_u64 v[24:25], v[82:83], 0, s[0:1]
	v_mov_b32_e32 v21, v20
	v_mov_b32_e32 v23, v22
	s_mov_b32 s78, 0
	v_mov_b32_e32 v91, v90

; #define LAS __attribute__((address_space(3)))
; __device__ __forceinline__ void ssm_pass3h(CArgs* ap, const float* COEF, int l, const bf16_t* PROJ, const float* SST, bf16_t* YS, LAS unsigned char* wlds, int unit, int lane) {
;     ...
;         for (int r = 0; r < 4; ++r) cmB[4 * j + r] = (j < 4) ? c4[r] : -c4[r];
;     ...
;     const size_t row0 = (size_t)(b * SEQ + c * 128);
;     const bf16_t* up = PROJ + row0 * INW + 2560 + g * 16;
;     LAS float* Hf = (LAS float*)wlds;
;     u32x4 wn[8];
; #pragma unroll
;     for (int tt = 0; tt < 4; ++tt) { wn[2 * tt] = ((const u32x4*)(up + (size_t)tt * INW))[0]; wn[2 * tt + 1] = ((const u32x4*)(up + (size_t)tt * INW))[1]; }
; #pragma unroll 1
;     for (int blk = 0; blk < 8; ++blk) {
;         unsigned short uq[4];
; #pragma unroll
;         for (int i = 0; i < 4; ++i) uq[i] = up[(size_t)(16 * blk + 4 * fq + i) * INW + fr];
.LBB0_148:
	s_lshl_b32 s0, s9, 2
	s_and_b32 s0, s0, 0xffffe000
	s_lshl_b32 s1, s3, 7
	s_or_b32 s0, s0, s1
	s_ashr_i32 s1, s0, 31
	s_mul_i32 s10, s0, 0x4800
	s_mul_hi_i32 s3, s0, 0x4800
	s_add_u32 s10, s68, s10
	s_addc_u32 s3, s69, s3
	s_lshl_b32 s78, s2, 1
	s_add_u32 s10, s10, s78
	s_addc_u32 s11, s3, 0
	s_add_u32 s2, s10, 0x1400
	s_addc_u32 s3, s11, 0
	s_add_u32 s12, s10, 0x5c00
	v_mov_b32_e32 v0, 0x5000
	global_load_dwordx4 v[20:23], v1, s[2:3] offset:16
	global_load_dwordx4 v[24:27], v198, s[10:11] offset:1024
	s_addc_u32 s13, s11, 0
	global_load_dwordx4 v[32:35], v0, s[10:11] offset:3072
	v_mov_b32_e32 v0, 0xa000
	global_load_dwordx4 v[28:31], v1, s[12:13] offset:16
	global_load_dwordx4 v[40:43], v0, s[10:11] offset:1024
	s_add_u32 s12, s10, 0xa400
	s_addc_u32 s13, s11, 0
	v_mov_b32_e32 v0, 0xe000
	global_load_dwordx4 v[36:39], v1, s[12:13] offset:16
	global_load_dwordx4 v[48:51], v0, s[10:11] offset:3072
	s_add_u32 s12, s10, 0xec00
	s_addc_u32 s13, s11, 0
	global_load_dwordx4 v[44:47], v1, s[12:13] offset:16
	v_lshl_add_u64 v[92:93], v[80:81], 0, s[78:79]
	v_pk_mov_b32 v[94:95], v[2:3], v[2:3] op_sel:[1,0]
	s_mov_b32 s10, 0
	s_waitcnt vmcnt(12)
	v_xor_b32_e32 v89, 0x80000000, v64
	v_xor_b32_e32 v117, 0x80000000, v65
	v_xor_b32_e32 v118, 0x80000000, v66
	v_xor_b32_e32 v119, 0x80000000, v67
	s_waitcnt vmcnt(11)
	v_xor_b32_e32 v120, 0x80000000, v60
	v_xor_b32_e32 v121, 0x80000000, v61
	v_xor_b32_e32 v122, 0x80000000, v62
	v_xor_b32_e32 v123, 0x80000000, v63
	s_waitcnt vmcnt(10)
	v_xor_b32_e32 v124, 0x80000000, v56
	v_xor_b32_e32 v125, 0x80000000, v57
	v_xor_b32_e32 v126, 0x80000000, v58
	v_xor_b32_e32 v127, 0x80000000, v59
	s_waitcnt vmcnt(9)
	v_xor_b32_e32 v128, 0x80000000, v52
	v_xor_b32_e32 v129, 0x80000000, v53
	v_xor_b32_e32 v130, 0x80000000, v54
	v_xor_b32_e32 v131, 0x80000000, v55
	s_add_u32 s14, s2, 0x12000
	s_addc_u32 s15, s3, 0
	global_load_dwordx4 v[208:211], v1, s[14:15] offset:16
	global_load_dwordx4 v[212:215], v1, s[14:15]
	s_add_u32 s14, s2, 0x16800
	s_addc_u32 s15, s3, 0
	global_load_dwordx4 v[216:219], v1, s[14:15] offset:16
	global_load_dwordx4 v[220:223], v1, s[14:15]
	s_add_u32 s14, s2, 0x1b000
	s_addc_u32 s15, s3, 0
	global_load_dwordx4 v[224:227], v1, s[14:15] offset:16
	global_load_dwordx4 v[228:231], v1, s[14:15]
	s_add_u32 s14, s2, 0x1f800
	s_addc_u32 s15, s3, 0
	global_load_dwordx4 v[232:235], v1, s[14:15] offset:16
	global_load_dwordx4 v[236:239], v1, s[14:15]
	s_mov_b32 s11, 0

; __device__ __forceinline__ void ssm_pass3h(CArgs* ap, const float* COEF, int l, const bf16_t* PROJ, const float* SST, bf16_t* YS, LAS unsigned char* wlds, int unit, int lane) {
;     ...
;         for (int q = 0; q < 4; ++q) {
;             const int t = 16 * blk + 4 * q;
;             u32x4 wc[8];
; #pragma unroll
;             for (int j = 0; j < 8; ++j) wc[j] = wn[j];
;             const int tn = (t + 4 < 128) ? t + 4 : t;
; #pragma unroll
;             for (int tt = 0; tt < 4; ++tt) { wn[2 * tt] = ((const u32x4*)(up + (size_t)(tn + tt) * INW))[0]; wn[2 * tt + 1] = ((const u32x4*)(up + (size_t)(tn + tt) * INW))[1]; }
; #pragma unroll
;             for (int tt = 0; tt < 4; ++tt) {
;                 const u32x4 w0 = wc[2 * tt], w1 = wc[2 * tt + 1];
;                 const unsigned u2[8] = {w0.x, w0.y, w0.z, w0.w, w1.x, w1.y, w1.z, w1.w};
;                 float br_ = 0.f, bi_ = 0.f;
; #pragma unroll
;                 for (int k = 0; k < 8; ++k) { br_ = __builtin_amdgcn_fdot2_f32_bf16(__builtin_bit_cast(bf16x2v, bbr2[k]), __builtin_bit_cast(bf16x2v, u2[k]), br_, false);
;                                                bi_ = __builtin_amdgcn_fdot2_f32_bf16(__builtin_bit_cast(bf16x2v, bbi2[k]), __builtin_bit_cast(bf16x2v, u2[k]), bi_, false); }
;                 const float nr = abr * hr - abi * hi + br_, ni = abr * hi + abi * hr + bi_; hr = nr; hi = ni;
;                 Hf[(4 * q + tt) * 132 + lane] = hr; Hf[(4 * q + tt) * 132 + 64 + lane] = hi;
;             }
.LBB0_150:
	s_add_i32 s13, s14, 4
	s_add_i32 s14, s14, 8
	s_min_u32 s14, s14, 0x7c
	s_mul_i32 s78, s14, 0x2400
	s_lshl_b64 s[14:15], s[78:79], 1
	s_add_u32 s14, s2, s14
	s_waitcnt vmcnt(15)
	v_mov_b64_e32 v[138:139], v[22:23]
	s_waitcnt vmcnt(14)
	v_mov_b64_e32 v[142:143], v[26:27]
	s_addc_u32 s15, s3, s15
	v_mov_b64_e32 v[136:137], v[20:21]
	v_mov_b64_e32 v[140:141], v[24:25]
	global_load_dwordx4 v[20:23], v1, s[14:15] offset:16
	global_load_dwordx4 v[24:27], v1, s[14:15]
	s_add_i32 s14, s78, 0x2400
	s_mov_b32 s15, s79
	s_lshl_b64 s[14:15], s[14:15], 1
	s_add_u32 s14, s2, s14
	s_waitcnt vmcnt(15)
	v_mov_b64_e32 v[70:71], v[30:31]
	s_waitcnt vmcnt(14)
	v_mov_b64_e32 v[74:75], v[34:35]
	s_addc_u32 s15, s3, s15
	v_mov_b64_e32 v[68:69], v[28:29]
	v_mov_b64_e32 v[72:73], v[32:33]
	global_load_dwordx4 v[28:31], v1, s[14:15] offset:16
	global_load_dwordx4 v[32:35], v1, s[14:15]
	s_add_i32 s14, s78, 0x4800
	s_mov_b32 s15, s79
	s_lshl_b64 s[14:15], s[14:15], 1
	s_add_u32 s14, s2, s14
	s_waitcnt vmcnt(15)
	v_mov_b64_e32 v[62:63], v[38:39]
	s_waitcnt vmcnt(14)
	v_mov_b64_e32 v[66:67], v[42:43]
	s_addc_u32 s15, s3, s15
	s_addk_i32 s78, 0x6c00
	v_mov_b64_e32 v[60:61], v[36:37]
	v_mov_b64_e32 v[64:65], v[40:41]
	global_load_dwordx4 v[36:39], v1, s[14:15] offset:16
	global_load_dwordx4 v[40:43], v1, s[14:15]
	s_lshl_b64 s[14:15], s[78:79], 1
	s_add_u32 s14, s2, s14
	s_waitcnt vmcnt(15)
	v_mov_b64_e32 v[54:55], v[46:47]
	s_waitcnt vmcnt(14)
	v_mov_b64_e32 v[58:59], v[50:51]
	s_addc_u32 s15, s3, s15
	v_mov_b64_e32 v[52:53], v[44:45]
	v_mov_b64_e32 v[56:57], v[48:49]
	global_load_dwordx4 v[44:47], v1, s[14:15] offset:16
	global_load_dwordx4 v[48:51], v1, s[14:15]
	v_mov_b32_e32 v0, 0
	v_dot2c_f32_bf16_e32 v0, v101, v140
	v_mov_b32_e32 v97, 0
	v_dot2c_f32_bf16_e32 v97, v102, v140
	v_dot2c_f32_bf16_e32 v0, v103, v141
	v_dot2c_f32_bf16_e32 v97, v104, v141
	v_dot2c_f32_bf16_e32 v0, v105, v142
	v_dot2c_f32_bf16_e32 v97, v106, v142
	v_dot2c_f32_bf16_e32 v0, v107, v143
	v_dot2c_f32_bf16_e32 v97, v108, v143
	v_dot2c_f32_bf16_e32 v0, v109, v136
	v_dot2c_f32_bf16_e32 v97, v110, v136
	v_dot2c_f32_bf16_e32 v0, v111, v137
	v_dot2c_f32_bf16_e32 v97, v112, v137
	v_dot2c_f32_bf16_e32 v0, v113, v138
	v_pk_mul_f32 v[136:137], v[2:3], v[90:91]
	v_dot2c_f32_bf16_e32 v0, v115, v139
	v_sub_f32_e32 v136, v136, v137
	v_mov_b32_e32 v137, 0
	v_dot2c_f32_bf16_e32 v137, v102, v72
	v_add_f32_e32 v0, v0, v136
	v_mov_b32_e32 v136, 0
	v_dot2c_f32_bf16_e32 v136, v101, v72
	v_dot2c_f32_bf16_e32 v136, v103, v73
	v_dot2c_f32_bf16_e32 v137, v104, v73
	v_dot2c_f32_bf16_e32 v136, v105, v74
	v_dot2c_f32_bf16_e32 v137, v106, v74
	v_dot2c_f32_bf16_e32 v136, v107, v75
	v_dot2c_f32_bf16_e32 v137, v108, v75
	v_dot2c_f32_bf16_e32 v136, v109, v68
	v_dot2c_f32_bf16_e32 v137, v110, v68
	v_dot2c_f32_bf16_e32 v136, v111, v69
	v_dot2c_f32_bf16_e32 v137, v112, v69
	v_mov_b32_e32 v68, 0
	v_mov_b32_e32 v69, 0
	v_dot2c_f32_bf16_e32 v68, v101, v64
	v_dot2c_f32_bf16_e32 v69, v102, v64
	v_dot2c_f32_bf16_e32 v68, v103, v65
	v_dot2c_f32_bf16_e32 v69, v104, v65
	v_dot2c_f32_bf16_e32 v68, v105, v66
	v_dot2c_f32_bf16_e32 v69, v106, v66
	v_dot2c_f32_bf16_e32 v97, v114, v138
	v_pk_mul_f32 v[90:91], v[94:95], v[90:91]
	v_dot2c_f32_bf16_e32 v68, v107, v67
	v_dot2c_f32_bf16_e32 v69, v108, v67
	v_dot2c_f32_bf16_e32 v97, v116, v139
	v_add_f32_e32 v90, v90, v91
	v_dot2c_f32_bf16_e32 v68, v109, v60
	v_dot2c_f32_bf16_e32 v69, v110, v60
	v_add_f32_e32 v90, v97, v90
	v_dot2c_f32_bf16_e32 v68, v111, v61
	v_dot2c_f32_bf16_e32 v69, v112, v61
	v_dot2c_f32_bf16_e32 v68, v113, v62
	v_dot2c_f32_bf16_e32 v69, v114, v62
	v_pk_mul_f32 v[60:61], v[94:95], v[90:91] op_sel_hi:[1,0]
	v_dot2c_f32_bf16_e32 v136, v113, v70
	v_dot2c_f32_bf16_e32 v137, v114, v70
	v_dot2c_f32_bf16_e32 v68, v115, v63
	v_dot2c_f32_bf16_e32 v69, v116, v63
	v_pk_fma_f32 v[62:63], v[2:3], v[0:1], v[60:61] neg_lo:[0,0,1] neg_hi:[0,0,1]
	v_pk_fma_f32 v[60:61], v[2:3], v[0:1], v[60:61] op_sel_hi:[1,0,1]
	v_dot2c_f32_bf16_e32 v136, v115, v71
	v_dot2c_f32_bf16_e32 v137, v116, v71
	v_mov_b32_e32 v63, v61
	v_add_u32_e32 v97, s12, v99
	ds_write2st64_b32 v97, v0, v90 offset1:1
	v_pk_add_f32 v[60:61], v[136:137], v[62:63]
	ds_write2_b32 v97, v60, v61 offset0:132 offset1:196
	v_pk_mul_f32 v[62:63], v[2:3], v[60:61]
	v_pk_mul_f32 v[60:61], v[2:3], v[60:61] op_sel:[0,1] op_sel_hi:[1,0]
	v_sub_f32_e32 v0, v62, v63
	v_mov_b32_e32 v62, 0
	v_mov_b32_e32 v63, 0
	v_dot2c_f32_bf16_e32 v62, v101, v56
	v_dot2c_f32_bf16_e32 v63, v102, v56
	v_dot2c_f32_bf16_e32 v62, v103, v57
	v_dot2c_f32_bf16_e32 v63, v104, v57
	v_dot2c_f32_bf16_e32 v62, v105, v58
	v_dot2c_f32_bf16_e32 v63, v106, v58
	v_dot2c_f32_bf16_e32 v62, v107, v59
	v_dot2c_f32_bf16_e32 v63, v108, v59
	v_add_f32_e32 v60, v60, v61
	v_dot2c_f32_bf16_e32 v62, v109, v52
	v_dot2c_f32_bf16_e32 v63, v110, v52
	v_add_f32_e32 v60, v69, v60
	v_add_u32_e32 v61, 32, v97
	v_dot2c_f32_bf16_e32 v62, v111, v53
	v_dot2c_f32_bf16_e32 v63, v112, v53
	v_add_f32_e32 v0, v68, v0
	v_dot2c_f32_bf16_e32 v62, v113, v54
	v_dot2c_f32_bf16_e32 v63, v114, v54
	v_pk_mul_f32 v[52:53], v[94:95], v[60:61] op_sel_hi:[1,0]
	v_dot2c_f32_bf16_e32 v62, v115, v55
	v_dot2c_f32_bf16_e32 v63, v116, v55
	v_pk_fma_f32 v[54:55], v[2:3], v[0:1], v[52:53] neg_lo:[0,0,1] neg_hi:[0,0,1]
	v_pk_fma_f32 v[52:53], v[2:3], v[0:1], v[52:53] op_sel_hi:[1,0,1]
	s_addk_i32 s12, 0x840
	v_mov_b32_e32 v55, v53
	ds_write2st64_b32 v61, v0, v60 offset0:4 offset1:5
	v_pk_add_f32 v[90:91], v[62:63], v[54:55]
	v_add_u32_e32 v0, 48, v97
	s_mov_b32 s14, s13
	ds_write2st64_b32 v0, v90, v91 offset0:6 offset1:7
	s_add_i32 s13, s14, 4
	s_add_i32 s14, s14, 8
	s_min_u32 s14, s14, 0x7c
	s_mul_i32 s78, s14, 0x2400
	s_lshl_b64 s[14:15], s[78:79], 1
	s_add_u32 s14, s2, s14
	s_waitcnt vmcnt(15)
; __device__ __forceinline__ void ssm_pass3h(CArgs* ap, const float* COEF, int l, const bf16_t* PROJ, const float* SST, bf16_t* YS, LAS unsigned char* wlds, int unit, int lane) {
;     ...
;         for (int q = 0; q < 4; ++q) {
;             const int t = 16 * blk + 4 * q;
;             u32x4 wc[8];
; #pragma unroll
;             for (int j = 0; j < 8; ++j) wc[j] = wn[j];
;             const int tn = (t + 4 < 128) ? t + 4 : t;
; #pragma unroll
;             for (int tt = 0; tt < 4; ++tt) { wn[2 * tt] = ((const u32x4*)(up + (size_t)(tn + tt) * INW))[0]; wn[2 * tt + 1] = ((const u32x4*)(up + (size_t)(tn + tt) * INW))[1]; }
; #pragma unroll
;             for (int tt = 0; tt < 4; ++tt) {
;                 const u32x4 w0 = wc[2 * tt], w1 = wc[2 * tt + 1];
;                 const unsigned u2[8] = {w0.x, w0.y, w0.z, w0.w, w1.x, w1.y, w1.z, w1.w};
;                 float br_ = 0.f, bi_ = 0.f;
; #pragma unroll
;                 for (int k = 0; k < 8; ++k) { br_ = __builtin_amdgcn_fdot2_f32_bf16(__builtin_bit_cast(bf16x2v, bbr2[k]), __builtin_bit_cast(bf16x2v, u2[k]), br_, false);
;                                                bi_ = __builtin_amdgcn_fdot2_f32_bf16(__builtin_bit_cast(bf16x2v, bbi2[k]), __builtin_bit_cast(bf16x2v, u2[k]), bi_, false); }
;                 const float nr = abr * hr - abi * hi + br_, ni = abr * hi + abi * hr + bi_; hr = nr; hi = ni;
;                 Hf[(4 * q + tt) * 132 + lane] = hr; Hf[(4 * q + tt) * 132 + 64 + lane] = hi;
;             }
	v_mov_b64_e32 v[138:139], v[210:211]
	s_waitcnt vmcnt(14)
	v_mov_b64_e32 v[142:143], v[214:215]
	s_addc_u32 s15, s3, s15
	v_mov_b64_e32 v[136:137], v[208:209]
	v_mov_b64_e32 v[140:141], v[212:213]
	global_load_dwordx4 v[208:211], v1, s[14:15] offset:16
	global_load_dwordx4 v[212:215], v1, s[14:15]
	s_add_i32 s14, s78, 0x2400
	s_mov_b32 s15, s79
	s_lshl_b64 s[14:15], s[14:15], 1
	s_add_u32 s14, s2, s14
	s_waitcnt vmcnt(15)
	v_mov_b64_e32 v[70:71], v[218:219]
	s_waitcnt vmcnt(14)
	v_mov_b64_e32 v[74:75], v[222:223]
	s_addc_u32 s15, s3, s15
	v_mov_b64_e32 v[68:69], v[216:217]
	v_mov_b64_e32 v[72:73], v[220:221]
	global_load_dwordx4 v[216:219], v1, s[14:15] offset:16
	global_load_dwordx4 v[220:223], v1, s[14:15]
	s_add_i32 s14, s78, 0x4800
	s_mov_b32 s15, s79
	s_lshl_b64 s[14:15], s[14:15], 1
	s_add_u32 s14, s2, s14
	s_waitcnt vmcnt(15)
	v_mov_b64_e32 v[62:63], v[226:227]
	s_waitcnt vmcnt(14)
	v_mov_b64_e32 v[66:67], v[230:231]
	s_addc_u32 s15, s3, s15
	s_addk_i32 s78, 0x6c00
	v_mov_b64_e32 v[60:61], v[224:225]
	v_mov_b64_e32 v[64:65], v[228:229]
	global_load_dwordx4 v[224:227], v1, s[14:15] offset:16
	global_load_dwordx4 v[228:231], v1, s[14:15]
	s_lshl_b64 s[14:15], s[78:79], 1
	s_add_u32 s14, s2, s14
	s_waitcnt vmcnt(15)
	v_mov_b64_e32 v[54:55], v[234:235]
	s_waitcnt vmcnt(14)
	v_mov_b64_e32 v[58:59], v[238:239]
	s_addc_u32 s15, s3, s15
	v_mov_b64_e32 v[52:53], v[232:233]
	v_mov_b64_e32 v[56:57], v[236:237]
	global_load_dwordx4 v[232:235], v1, s[14:15] offset:16
	global_load_dwordx4 v[236:239], v1, s[14:15]
	v_mov_b32_e32 v0, 0
	v_dot2c_f32_bf16_e32 v0, v101, v140
	v_mov_b32_e32 v97, 0
	v_dot2c_f32_bf16_e32 v97, v102, v140
	v_dot2c_f32_bf16_e32 v0, v103, v141
	v_dot2c_f32_bf16_e32 v97, v104, v141
	v_dot2c_f32_bf16_e32 v0, v105, v142
	v_dot2c_f32_bf16_e32 v97, v106, v142
	v_dot2c_f32_bf16_e32 v0, v107, v143
	v_dot2c_f32_bf16_e32 v97, v108, v143
	v_dot2c_f32_bf16_e32 v0, v109, v136
	v_dot2c_f32_bf16_e32 v97, v110, v136
	v_dot2c_f32_bf16_e32 v0, v111, v137
	v_dot2c_f32_bf16_e32 v97, v112, v137
	v_dot2c_f32_bf16_e32 v0, v113, v138
	v_pk_mul_f32 v[136:137], v[2:3], v[90:91]
	v_dot2c_f32_bf16_e32 v0, v115, v139
	v_sub_f32_e32 v136, v136, v137
	v_mov_b32_e32 v137, 0
	v_dot2c_f32_bf16_e32 v137, v102, v72
	v_add_f32_e32 v0, v0, v136
	v_mov_b32_e32 v136, 0
	v_dot2c_f32_bf16_e32 v136, v101, v72
	v_dot2c_f32_bf16_e32 v136, v103, v73
	v_dot2c_f32_bf16_e32 v137, v104, v73
	v_dot2c_f32_bf16_e32 v136, v105, v74
	v_dot2c_f32_bf16_e32 v137, v106, v74
	v_dot2c_f32_bf16_e32 v136, v107, v75
	v_dot2c_f32_bf16_e32 v137, v108, v75
	v_dot2c_f32_bf16_e32 v136, v109, v68
	v_dot2c_f32_bf16_e32 v137, v110, v68
	v_dot2c_f32_bf16_e32 v136, v111, v69
	v_dot2c_f32_bf16_e32 v137, v112, v69
	v_mov_b32_e32 v68, 0
	v_mov_b32_e32 v69, 0
	v_dot2c_f32_bf16_e32 v68, v101, v64
	v_dot2c_f32_bf16_e32 v69, v102, v64
	v_dot2c_f32_bf16_e32 v68, v103, v65
	v_dot2c_f32_bf16_e32 v69, v104, v65
	v_dot2c_f32_bf16_e32 v68, v105, v66
	v_dot2c_f32_bf16_e32 v69, v106, v66
	v_dot2c_f32_bf16_e32 v97, v114, v138
	v_pk_mul_f32 v[90:91], v[94:95], v[90:91]
	v_dot2c_f32_bf16_e32 v68, v107, v67
	v_dot2c_f32_bf16_e32 v69, v108, v67
	v_dot2c_f32_bf16_e32 v97, v116, v139
	v_add_f32_e32 v90, v90, v91
	v_dot2c_f32_bf16_e32 v68, v109, v60
	v_dot2c_f32_bf16_e32 v69, v110, v60
	v_add_f32_e32 v90, v97, v90
	v_dot2c_f32_bf16_e32 v68, v111, v61
	v_dot2c_f32_bf16_e32 v69, v112, v61
	v_dot2c_f32_bf16_e32 v68, v113, v62
	v_dot2c_f32_bf16_e32 v69, v114, v62
	v_pk_mul_f32 v[60:61], v[94:95], v[90:91] op_sel_hi:[1,0]
	v_dot2c_f32_bf16_e32 v136, v113, v70
	v_dot2c_f32_bf16_e32 v137, v114, v70
	v_dot2c_f32_bf16_e32 v68, v115, v63
	v_dot2c_f32_bf16_e32 v69, v116, v63
	v_pk_fma_f32 v[62:63], v[2:3], v[0:1], v[60:61] neg_lo:[0,0,1] neg_hi:[0,0,1]
	v_pk_fma_f32 v[60:61], v[2:3], v[0:1], v[60:61] op_sel_hi:[1,0,1]
	v_dot2c_f32_bf16_e32 v136, v115, v71
	v_dot2c_f32_bf16_e32 v137, v116, v71
	v_mov_b32_e32 v63, v61
	v_add_u32_e32 v97, s12, v99
	ds_write2st64_b32 v97, v0, v90 offset1:1
	v_pk_add_f32 v[60:61], v[136:137], v[62:63]
	ds_write2_b32 v97, v60, v61 offset0:132 offset1:196
	v_pk_mul_f32 v[62:63], v[2:3], v[60:61]
	v_pk_mul_f32 v[60:61], v[2:3], v[60:61] op_sel:[0,1] op_sel_hi:[1,0]
	v_sub_f32_e32 v0, v62, v63
	v_mov_b32_e32 v62, 0
	v_mov_b32_e32 v63, 0
	v_dot2c_f32_bf16_e32 v62, v101, v56
	v_dot2c_f32_bf16_e32 v63, v102, v56
	v_dot2c_f32_bf16_e32 v62, v103, v57
	v_dot2c_f32_bf16_e32 v63, v104, v57
	v_dot2c_f32_bf16_e32 v62, v105, v58
	v_dot2c_f32_bf16_e32 v63, v106, v58
	v_dot2c_f32_bf16_e32 v62, v107, v59
	v_dot2c_f32_bf16_e32 v63, v108, v59
	v_add_f32_e32 v60, v60, v61
	v_dot2c_f32_bf16_e32 v62, v109, v52
	v_dot2c_f32_bf16_e32 v63, v110, v52
	v_add_f32_e32 v60, v69, v60
	v_add_u32_e32 v61, 32, v97
	v_dot2c_f32_bf16_e32 v62, v111, v53
	v_dot2c_f32_bf16_e32 v63, v112, v53
	v_add_f32_e32 v0, v68, v0
	v_dot2c_f32_bf16_e32 v62, v113, v54
	v_dot2c_f32_bf16_e32 v63, v114, v54
	v_pk_mul_f32 v[52:53], v[94:95], v[60:61] op_sel_hi:[1,0]
	v_dot2c_f32_bf16_e32 v62, v115, v55
	v_dot2c_f32_bf16_e32 v63, v116, v55
	v_pk_fma_f32 v[54:55], v[2:3], v[0:1], v[52:53] neg_lo:[0,0,1] neg_hi:[0,0,1]
	v_pk_fma_f32 v[52:53], v[2:3], v[0:1], v[52:53] op_sel_hi:[1,0,1]
	s_addk_i32 s12, 0x840
	v_mov_b32_e32 v55, v53
	ds_write2st64_b32 v61, v0, v60 offset0:4 offset1:5
	v_pk_add_f32 v[90:91], v[62:63], v[54:55]
	v_add_u32_e32 v0, 48, v97
	s_cmpk_eq_i32 s12, 0x2100
	s_mov_b32 s14, s13
	ds_write2st64_b32 v0, v90, v91 offset0:6 offset1:7
	s_cbranch_scc0 .LBB0_150
; __device__ __forceinline__ float gelu_t(float x) { const float p = __builtin_fmaf(x * x, -0.10294324f, -2.30220819f); return x * __builtin_amdgcn_rcpf(1.f + __builtin_amdgcn_exp2f(x * p)); }
; #define LAS __attribute__((address_space(3)))
; __device__ __forceinline__ unsigned f2bf(float f) { unsigned u = __builtin_bit_cast(unsigned, f); return (u + 0x7fffu + ((u >> 16) & 1u)) >> 16; }
; __device__ __forceinline__ void ssm_pass3h(CArgs* ap, const float* COEF, int l, const bf16_t* PROJ, const float* SST, bf16_t* YS, LAS unsigned char* wlds, int unit, int lane) {
;     ...
;         asm volatile("s_waitcnt lgkmcnt(0)" ::: "memory");
;         f32x4 y = (f32x4){0.f, 0.f, 0.f, 0.f};
; #pragma unroll
;         for (int j = 0; j < 8; ++j) {
;             const f32x4 a4 = *(const LAS f32x4*)(Hf + fr * 132 + 16 * j + 4 * fq);
; #pragma unroll
;             for (int r = 0; r < 4; ++r) y = __builtin_amdgcn_mfma_f32_16x16x4f32(a4[r], cmB[4 * j + r], y, 0, 0, 0);
;         }
;         asm volatile("s_waitcnt lgkmcnt(0)" ::: "memory");
; #pragma unroll
;         for (int i = 0; i < 4; ++i) {
;             const size_t row = row0 + 16 * blk + 4 * fq + i;
;             YS[row * 512 + g * 16 + fr] = (bf16_t)f2bf(gelu_t(y[i] + dsk * __uint_as_float(((unsigned)uq[i]) << 16)));
;         }
	s_waitcnt lgkmcnt(0)
	ds_read_b128 v[144:147], v100
	ds_read_b128 v[148:151], v100 offset:64
	ds_read_b128 v[152:155], v100 offset:128
	ds_read_b128 v[168:171], v100 offset:192
	ds_read_b128 v[172:175], v100 offset:256
	ds_read_b128 v[176:179], v100 offset:320
	ds_read_b128 v[180:183], v100 offset:384
	ds_read_b128 v[184:187], v100 offset:448
	s_waitcnt vmcnt(19)
	v_lshlrev_b32_e32 v57, 16, v135
	v_mov_b32_e32 v97, v1
	v_or_b32_e32 v0, 1, v96
	v_or_b32_e32 v58, 2, v96
	v_mov_b32_e32 v59, v1
	v_or_b32_e32 v56, 3, v96
	s_add_i32 s11, s11, 1
	s_add_i32 s10, s10, 16
	s_cmp_eq_u32 s11, 8
	v_lshl_add_u64 v[60:61], v[96:97], 0, s[0:1]
	v_lshlrev_b64 v[60:61], 10, v[60:61]
	v_lshl_add_u64 v[60:61], v[92:93], 0, v[60:61]
	s_waitcnt lgkmcnt(6)
	v_mfma_f32_16x16x4_f32 v[52:55], v144, v4, 0
	v_mfma_f32_16x16x4_f32 v[188:191], v148, v8, 0
	v_mfma_f32_16x16x4_f32 v[52:55], v145, v5, v[52:55]
	v_mfma_f32_16x16x4_f32 v[188:191], v149, v9, v[188:191]
	v_mfma_f32_16x16x4_f32 v[52:55], v146, v6, v[52:55]
	v_mfma_f32_16x16x4_f32 v[188:191], v150, v10, v[188:191]
	v_mfma_f32_16x16x4_f32 v[52:55], v147, v7, v[52:55]
	v_mfma_f32_16x16x4_f32 v[188:191], v151, v11, v[188:191]
	s_waitcnt lgkmcnt(4)
	v_mfma_f32_16x16x4_f32 v[52:55], v152, v12, v[52:55]
	v_mfma_f32_16x16x4_f32 v[188:191], v168, v16, v[188:191]
	v_mfma_f32_16x16x4_f32 v[52:55], v153, v13, v[52:55]
	v_mfma_f32_16x16x4_f32 v[188:191], v169, v17, v[188:191]
	v_mfma_f32_16x16x4_f32 v[52:55], v154, v14, v[52:55]
	v_mfma_f32_16x16x4_f32 v[188:191], v170, v18, v[188:191]
	v_mfma_f32_16x16x4_f32 v[52:55], v155, v15, v[52:55]
	v_mfma_f32_16x16x4_f32 v[188:191], v171, v19, v[188:191]
	s_waitcnt lgkmcnt(2)
	v_mfma_f32_16x16x4_f32 v[52:55], v172, v89, v[52:55]
	v_mfma_f32_16x16x4_f32 v[188:191], v176, v120, v[188:191]
	v_mfma_f32_16x16x4_f32 v[52:55], v173, v117, v[52:55]
	v_mfma_f32_16x16x4_f32 v[188:191], v177, v121, v[188:191]
	v_mfma_f32_16x16x4_f32 v[52:55], v174, v118, v[52:55]
	v_mfma_f32_16x16x4_f32 v[188:191], v178, v122, v[188:191]
	v_mfma_f32_16x16x4_f32 v[52:55], v175, v119, v[52:55]
	v_mfma_f32_16x16x4_f32 v[188:191], v179, v123, v[188:191]
	s_waitcnt lgkmcnt(0)
	v_mfma_f32_16x16x4_f32 v[52:55], v180, v124, v[52:55]
	v_mfma_f32_16x16x4_f32 v[188:191], v184, v128, v[188:191]
	v_mfma_f32_16x16x4_f32 v[52:55], v181, v125, v[52:55]
	v_mfma_f32_16x16x4_f32 v[188:191], v185, v129, v[188:191]
	v_mfma_f32_16x16x4_f32 v[52:55], v182, v126, v[52:55]
	v_mfma_f32_16x16x4_f32 v[188:191], v186, v130, v[188:191]
	v_mfma_f32_16x16x4_f32 v[52:55], v183, v127, v[52:55]
	v_mfma_f32_16x16x4_f32 v[188:191], v187, v131, v[188:191]
	s_nop 9
	s_nop 1
	v_add_f32_e32 v52, v52, v188
	v_add_f32_e32 v53, v53, v189
	v_add_f32_e32 v54, v54, v190
	v_add_f32_e32 v55, v55, v191
	v_fma_f32 v52, v87, v57, v52
	v_mul_f32_e32 v57, v52, v52
	v_fmamk_f32 v57, v57, 0xbdd2d3e8, v196
	v_mul_f32_e32 v57, v52, v57
	v_exp_f32_e32 v57, v57
	s_nop 0
	v_add_f32_e32 v57, 1.0, v57
	v_rcp_f32_e32 v57, v57
	s_nop 0
	v_mul_f32_e32 v52, v52, v57
	v_bfe_u32 v57, v52, 16, 1
	v_add3_u32 v52, v52, v57, s80
	global_store_short_d16_hi v[60:61], v52, off
	v_lshl_add_u64 v[60:61], v[0:1], 0, s[0:1]
	s_waitcnt vmcnt(19)
	v_lshlrev_b32_e32 v0, 16, v134
	v_fma_f32 v0, v87, v0, v53
	v_mul_f32_e32 v52, v0, v0
	v_fmamk_f32 v52, v52, 0xbdd2d3e8, v196
	v_mul_f32_e32 v52, v0, v52
	v_exp_f32_e32 v52, v52
	v_mov_b32_e32 v57, v1
	v_add_f32_e32 v52, 1.0, v52
	v_rcp_f32_e32 v52, v52
	s_nop 0
	v_mul_f32_e32 v0, v0, v52
	v_bfe_u32 v52, v0, 16, 1
	v_add3_u32 v0, v0, v52, s80
	v_lshlrev_b64 v[52:53], 10, v[60:61]
	v_lshl_add_u64 v[52:53], v[92:93], 0, v[52:53]
	global_store_short_d16_hi v[52:53], v0, off
	s_waitcnt vmcnt(19)
	v_lshlrev_b32_e32 v0, 16, v133
	v_fma_f32 v0, v87, v0, v54
	v_mul_f32_e32 v54, v0, v0
	v_fmamk_f32 v54, v54, 0xbdd2d3e8, v196
	v_mul_f32_e32 v54, v0, v54
	v_exp_f32_e32 v54, v54
	v_lshl_add_u64 v[52:53], v[58:59], 0, s[0:1]
	v_lshlrev_b64 v[52:53], 10, v[52:53]
	v_lshl_add_u64 v[52:53], v[92:93], 0, v[52:53]
	v_add_f32_e32 v54, 1.0, v54
	v_rcp_f32_e32 v54, v54
	s_nop 0
	v_mul_f32_e32 v0, v0, v54
	v_bfe_u32 v54, v0, 16, 1
	v_add3_u32 v0, v0, v54, s80
	global_store_short_d16_hi v[52:53], v0, off
	s_waitcnt vmcnt(19)
	v_lshlrev_b32_e32 v0, 16, v132
	v_fmac_f32_e32 v55, v87, v0
	v_mul_f32_e32 v0, v55, v55
	v_fmamk_f32 v0, v0, 0xbdd2d3e8, v196
	v_mul_f32_e32 v0, v55, v0
	v_exp_f32_e32 v0, v0
	v_lshl_add_u64 v[52:53], v[56:57], 0, s[0:1]
	v_lshlrev_b64 v[52:53], 10, v[52:53]
	v_lshl_add_u64 v[52:53], v[92:93], 0, v[52:53]
	v_add_f32_e32 v0, 1.0, v0
	v_rcp_f32_e32 v0, v0
	s_nop 0
	v_mul_f32_e32 v0, v55, v0
	v_bfe_u32 v54, v0, 16, 1
	v_add3_u32 v0, v0, v54, s80
	global_store_short_d16_hi v[52:53], v0, off
	s_cbranch_scc0 .LBB0_149
	s_add_i32 s9, s9, s33
	s_cmpk_gt_i32 s9, 0xfff
	s_cbranch_scc0 .LBB0_141
